# v18 = v17 + remaining slow-path v_pk_add_f32 between MFMAs split into scalar pairs (6 sites)
# baseline (speedup 1.0000x reference)
; DI int crow(int r, int h) { return (r & 3) + 8 * (r >> 2) + 4 * h; }
; DI void attn_item(const Params& p, int g, int seq, int hd, int qt, int m, char* smem, int split_j, int sub) {
;     ...
;   auto rescale = [&](float f) __attribute__((always_inline)) {
; #pragma unroll
;     for (int dt = 0; dt < 4; ++dt)
; #pragma unroll
;       for (int r = 0; r < 16; ++r) O[dt][r] *= f;
;     ls2 *= f;
;   };
;   auto compute = [&](int st, int buf) __attribute__((always_inline)) {
;     const int k0 = (tbase + st) * 32, h = h_, l31 = l31_;
;     const bf16_t* Kb = Ks + buf * 32 * 72; const bf16_t* Vb = Vs + buf * 128 * 40;
;     const int rmin = k0 - (qw0 + 31), rmax = k0 + 31 - qw0;
;     const bool farL = rmax <= -128, farR = rmin >= 128;
;     if (!farL && region == 0) { rescale(__builtin_amdgcn_exp2f(cneg)); region = 1; }
;     if (farR && region == 1) { rescale(__builtin_amdgcn_exp2f(-cpos)); region = 2; }
;     bf16x8 kf[4], vf[2][4];
; #pragma unroll
;     for (int s = 0; s < 4; ++s) kf[s] = *(const bf16x8*)(Kb + l31 * 72 + s * 16 + h * 8);
; #pragma unroll
;     for (int s2 = 0; s2 < 2; ++s2)
; #pragma unroll
;       for (int dt = 0; dt < 4; ++dt) vf[s2][dt] = *(const bf16x8*)(Vb + (dt * 32 + l31) * 40 + s2 * 16 + h * 8);
;     __builtin_amdgcn_sched_barrier(0);
;     f32x16 X;
; #pragma unroll
;     for (int r = 0; r < 16; ++r) X[r] = 0.f;
; #pragma unroll
;     for (int s = 0; s < 4; ++s) X = MFMA32(kf[s], qf[s], X);
;     if (farL || farR) {
; #pragma unroll
;       for (int r = 0; r < 16; ++r) X[r] = __builtin_amdgcn_exp2f(X[r]);
;     } else {
;       const int rel0 = k0 - (qw0 + l31) + 128;
; #pragma unroll
;       for (int r = 0; r < 16; ++r) { int idx = rel0 + crow(r, h); idx = idx < 0 ? 0 : (idx > 256 ? 256 : idx); X[r] = __builtin_amdgcn_exp2f(X[r] + tab[idx]); }
;     }
;     bf16x8 pf[2];
; #pragma unroll
;     for (int s2 = 0; s2 < 2; ++s2) {
;       u32x4 w; w.x = pk_bf16(X[8 * s2], X[8 * s2 + 1]); w.y = pk_bf16(X[8 * s2 + 2], X[8 * s2 + 3]); w.z = pk_bf16(X[8 * s2 + 4], X[8 * s2 + 5]); w.w = pk_bf16(X[8 * s2 + 6], X[8 * s2 + 7]);
;       ls2 += (f32x2){X[8 * s2], X[8 * s2 + 1]}; ls2 += (f32x2){X[8 * s2 + 2], X[8 * s2 + 3]};
;       ls2 += (f32x2){X[8 * s2 + 4], X[8 * s2 + 5]}; ls2 += (f32x2){X[8 * s2 + 6], X[8 * s2 + 7]};
;       pf[s2] = __builtin_bit_cast(bf16x8, w);
;     }
; #pragma unroll
;     for (int s2 = 0; s2 < 2; ++s2)
; #pragma unroll
.LBB0_276:
	v_cvt_pk_bf16_f32 v64, v80, v81
	v_cvt_pk_bf16_f32 v65, v82, v83
	v_cvt_pk_bf16_f32 v66, v84, v85
	v_cvt_pk_bf16_f32 v67, v86, v87
	v_exp_f32_e32 v95, v79
	v_add_f32_e32 v68, v186, v80
	v_add_f32_e32 v69, v187, v81
	s_waitcnt lgkmcnt(7)
	v_mfma_f32_32x32x16_bf16 v[16:31], v[64:67], v[156:159], v[16:31]
	v_add_f32_e64 v68, v82, v68
	v_add_f32_e64 v69, v83, v69
	v_cvt_pk_bf16_f32 v70, v92, v93
	v_add_f32_e64 v68, v84, v68
	v_add_f32_e64 v69, v85, v69
	v_cvt_pk_bf16_f32 v71, v94, v95
	v_add_f32_e32 v72, v86, v68
	v_add_f32_e32 v73, v87, v69
	v_cvt_pk_bf16_f32 v68, v88, v89
	v_cvt_pk_bf16_f32 v69, v90, v91
	s_waitcnt lgkmcnt(5)
	v_mfma_f32_32x32x16_bf16 v[32:47], v[64:67], v[160:163], v[32:47]
	s_add_i32 s8, s17, 63
	s_cmpk_lt_i32 s8, 0xff81
	v_add_f32_e64 v72, v88, v72
	v_add_f32_e64 v73, v89, v73
	s_cselect_b64 s[8:9], -1, 0
	s_cmp_lg_u32 s16, 0
	v_add_f32_e32 v72, v90, v72
	v_add_f32_e32 v73, v91, v73
	s_cselect_b64 s[20:21], -1, 0
	s_waitcnt lgkmcnt(3)
	v_mfma_f32_32x32x16_bf16 v[48:63], v[64:67], v[164:167], v[48:63]
	v_add_f32_e64 v72, v92, v72
	v_add_f32_e64 v73, v93, v73
	s_or_b64 s[8:9], s[8:9], s[20:21]
	v_add_f32_e64 v186, v94, v72
	v_add_f32_e64 v187, v95, v73
	s_and_b64 vcc, exec, s[8:9]
	s_waitcnt lgkmcnt(1)
	v_mfma_f32_32x32x16_bf16 v[0:15], v[64:67], v[152:155], v[0:15]
	v_mfma_f32_32x32x16_bf16 v[16:31], v[68:71], v[148:151], v[16:31]
	v_mfma_f32_32x32x16_bf16 v[32:47], v[68:71], v[144:147], v[32:47]
	v_mfma_f32_32x32x16_bf16 v[48:63], v[68:71], v[136:139], v[48:63]
	s_waitcnt lgkmcnt(0)
	v_mfma_f32_32x32x16_bf16 v[0:15], v[68:71], v[140:143], v[0:15]
	s_cbranch_vccnz .LBB0_278
	v_mov_b32_e32 v171, v170
	s_nop 5
	v_pk_mul_f32 v[30:31], v[170:171], v[30:31]
	v_pk_mul_f32 v[28:29], v[170:171], v[28:29]
	v_pk_mul_f32 v[26:27], v[170:171], v[26:27]
	v_pk_mul_f32 v[24:25], v[170:171], v[24:25]
	v_pk_mul_f32 v[22:23], v[170:171], v[22:23]
	v_pk_mul_f32 v[20:21], v[170:171], v[20:21]
	v_pk_mul_f32 v[18:19], v[170:171], v[18:19]
	v_pk_mul_f32 v[16:17], v[174:175], v[16:17]
	v_pk_mul_f32 v[46:47], v[170:171], v[46:47]
	v_pk_mul_f32 v[44:45], v[170:171], v[44:45]
	v_pk_mul_f32 v[42:43], v[170:171], v[42:43]
	v_pk_mul_f32 v[40:41], v[170:171], v[40:41]
	v_pk_mul_f32 v[38:39], v[170:171], v[38:39]
	v_pk_mul_f32 v[36:37], v[170:171], v[36:37]
	v_pk_mul_f32 v[34:35], v[170:171], v[34:35]
	v_pk_mul_f32 v[32:33], v[174:175], v[32:33]
	v_pk_mul_f32 v[62:63], v[170:171], v[62:63]
	v_pk_mul_f32 v[60:61], v[170:171], v[60:61]
	v_pk_mul_f32 v[58:59], v[170:171], v[58:59]
	v_pk_mul_f32 v[56:57], v[170:171], v[56:57]
	v_pk_mul_f32 v[54:55], v[170:171], v[54:55]
	v_pk_mul_f32 v[52:53], v[170:171], v[52:53]
	v_pk_mul_f32 v[50:51], v[170:171], v[50:51]
	v_pk_mul_f32 v[48:49], v[174:175], v[48:49]
	v_pk_mul_f32 v[14:15], v[170:171], v[14:15]
	v_pk_mul_f32 v[12:13], v[170:171], v[12:13]
	v_pk_mul_f32 v[10:11], v[170:171], v[10:11]
	v_pk_mul_f32 v[8:9], v[170:171], v[8:9]
	v_pk_mul_f32 v[6:7], v[170:171], v[6:7]
	v_pk_mul_f32 v[4:5], v[170:171], v[4:5]
	v_pk_mul_f32 v[2:3], v[170:171], v[2:3]
	v_pk_mul_f32 v[0:1], v[174:175], v[0:1]
	v_pk_mul_f32 v[186:187], v[172:173], v[186:187]
	s_mov_b32 s16, 1

; DI int crow(int r, int h) { return (r & 3) + 8 * (r >> 2) + 4 * h; }
; DI void attn_item(const Params& p, int g, int seq, int hd, int qt, int m, char* smem, int split_j, int sub) {
;     ...
;   auto rescale = [&](float f) __attribute__((always_inline)) {
; #pragma unroll
;     for (int dt = 0; dt < 4; ++dt)
; #pragma unroll
;       for (int r = 0; r < 16; ++r) O[dt][r] *= f;
;     ls2 *= f;
;   };
;   auto compute = [&](int st, int buf) __attribute__((always_inline)) {
;     const int k0 = (tbase + st) * 32, h = h_, l31 = l31_;
;     const bf16_t* Kb = Ks + buf * 32 * 72; const bf16_t* Vb = Vs + buf * 128 * 40;
;     const int rmin = k0 - (qw0 + 31), rmax = k0 + 31 - qw0;
;     const bool farL = rmax <= -128, farR = rmin >= 128;
;     if (!farL && region == 0) { rescale(__builtin_amdgcn_exp2f(cneg)); region = 1; }
;     if (farR && region == 1) { rescale(__builtin_amdgcn_exp2f(-cpos)); region = 2; }
;     bf16x8 kf[4], vf[2][4];
; #pragma unroll
;     for (int s = 0; s < 4; ++s) kf[s] = *(const bf16x8*)(Kb + l31 * 72 + s * 16 + h * 8);
; #pragma unroll
;     for (int s2 = 0; s2 < 2; ++s2)
; #pragma unroll
;       for (int dt = 0; dt < 4; ++dt) vf[s2][dt] = *(const bf16x8*)(Vb + (dt * 32 + l31) * 40 + s2 * 16 + h * 8);
;     __builtin_amdgcn_sched_barrier(0);
;     f32x16 X;
; #pragma unroll
;     for (int r = 0; r < 16; ++r) X[r] = 0.f;
; #pragma unroll
;     for (int s = 0; s < 4; ++s) X = MFMA32(kf[s], qf[s], X);
;     if (farL || farR) {
; #pragma unroll
;       for (int r = 0; r < 16; ++r) X[r] = __builtin_amdgcn_exp2f(X[r]);
;     } else {
;       const int rel0 = k0 - (qw0 + l31) + 128;
; #pragma unroll
;       for (int r = 0; r < 16; ++r) { int idx = rel0 + crow(r, h); idx = idx < 0 ? 0 : (idx > 256 ? 256 : idx); X[r] = __builtin_amdgcn_exp2f(X[r] + tab[idx]); }
;     }
;     bf16x8 pf[2];
; #pragma unroll
;     for (int s2 = 0; s2 < 2; ++s2) {
;       u32x4 w; w.x = pk_bf16(X[8 * s2], X[8 * s2 + 1]); w.y = pk_bf16(X[8 * s2 + 2], X[8 * s2 + 3]); w.z = pk_bf16(X[8 * s2 + 4], X[8 * s2 + 5]); w.w = pk_bf16(X[8 * s2 + 6], X[8 * s2 + 7]);
;       ls2 += (f32x2){X[8 * s2], X[8 * s2 + 1]}; ls2 += (f32x2){X[8 * s2 + 2], X[8 * s2 + 3]};
;       ls2 += (f32x2){X[8 * s2 + 4], X[8 * s2 + 5]}; ls2 += (f32x2){X[8 * s2 + 6], X[8 * s2 + 7]};
;       pf[s2] = __builtin_bit_cast(bf16x8, w);
;     }
; #pragma unroll
;     for (int s2 = 0; s2 < 2; ++s2)
; #pragma unroll
.LBB0_327:
	v_cvt_pk_bf16_f32 v64, v80, v81
	v_cvt_pk_bf16_f32 v65, v82, v83
	v_cvt_pk_bf16_f32 v66, v84, v85
	v_cvt_pk_bf16_f32 v67, v86, v87
	v_exp_f32_e32 v95, v79
	v_add_f32_e32 v68, v186, v80
	v_add_f32_e32 v69, v187, v81
	s_waitcnt lgkmcnt(7)
	v_mfma_f32_32x32x16_bf16 v[48:63], v[64:67], v[156:159], v[48:63]
	v_add_f32_e64 v68, v82, v68
	v_add_f32_e64 v69, v83, v69
	v_cvt_pk_bf16_f32 v70, v92, v93
	v_add_f32_e64 v68, v84, v68
	v_add_f32_e64 v69, v85, v69
	v_cvt_pk_bf16_f32 v71, v94, v95
	v_add_f32_e32 v72, v86, v68
	v_add_f32_e32 v73, v87, v69
	v_cvt_pk_bf16_f32 v68, v88, v89
	v_cvt_pk_bf16_f32 v69, v90, v91
	s_waitcnt lgkmcnt(5)
	v_mfma_f32_32x32x16_bf16 v[32:47], v[64:67], v[160:163], v[32:47]
	s_add_i32 s10, s7, 63
	s_cmpk_lt_i32 s10, 0xff81
	v_add_f32_e64 v72, v88, v72
	v_add_f32_e64 v73, v89, v73
	s_cselect_b64 s[10:11], -1, 0
	s_cmp_lg_u32 s17, 0
	v_add_f32_e32 v72, v90, v72
	v_add_f32_e32 v73, v91, v73
	s_cselect_b64 s[20:21], -1, 0
	s_waitcnt lgkmcnt(3)
	v_mfma_f32_32x32x16_bf16 v[16:31], v[64:67], v[164:167], v[16:31]
	v_add_f32_e64 v72, v92, v72
	v_add_f32_e64 v73, v93, v73
	s_or_b64 s[10:11], s[10:11], s[20:21]
	v_add_f32_e64 v186, v94, v72
	v_add_f32_e64 v187, v95, v73
	s_and_b64 vcc, exec, s[10:11]
	s_waitcnt lgkmcnt(1)
	v_mfma_f32_32x32x16_bf16 v[0:15], v[64:67], v[152:155], v[0:15]
	v_mfma_f32_32x32x16_bf16 v[48:63], v[68:71], v[148:151], v[48:63]
	v_mfma_f32_32x32x16_bf16 v[32:47], v[68:71], v[144:147], v[32:47]
	v_mfma_f32_32x32x16_bf16 v[16:31], v[68:71], v[136:139], v[16:31]
	s_waitcnt lgkmcnt(0)
	v_mfma_f32_32x32x16_bf16 v[0:15], v[68:71], v[140:143], v[0:15]
	s_cbranch_vccnz .LBB0_329
	v_mov_b32_e32 v175, v174
	s_nop 5
	v_pk_mul_f32 v[62:63], v[174:175], v[62:63]
	v_pk_mul_f32 v[60:61], v[174:175], v[60:61]
	v_pk_mul_f32 v[58:59], v[174:175], v[58:59]
	v_pk_mul_f32 v[56:57], v[174:175], v[56:57]
	v_pk_mul_f32 v[54:55], v[174:175], v[54:55]
	v_pk_mul_f32 v[52:53], v[174:175], v[52:53]
	v_pk_mul_f32 v[50:51], v[174:175], v[50:51]
	v_pk_mul_f32 v[48:49], v[182:183], v[48:49]
	v_pk_mul_f32 v[46:47], v[174:175], v[46:47]
	v_pk_mul_f32 v[44:45], v[174:175], v[44:45]
	v_pk_mul_f32 v[42:43], v[174:175], v[42:43]
	v_pk_mul_f32 v[40:41], v[174:175], v[40:41]
	v_pk_mul_f32 v[38:39], v[174:175], v[38:39]
	v_pk_mul_f32 v[36:37], v[174:175], v[36:37]
	v_pk_mul_f32 v[34:35], v[174:175], v[34:35]
	v_pk_mul_f32 v[32:33], v[182:183], v[32:33]
	v_pk_mul_f32 v[30:31], v[174:175], v[30:31]
	v_pk_mul_f32 v[28:29], v[174:175], v[28:29]
	v_pk_mul_f32 v[26:27], v[174:175], v[26:27]
	v_pk_mul_f32 v[24:25], v[174:175], v[24:25]
	v_pk_mul_f32 v[22:23], v[174:175], v[22:23]
	v_pk_mul_f32 v[20:21], v[174:175], v[20:21]
	v_pk_mul_f32 v[18:19], v[174:175], v[18:19]
	v_pk_mul_f32 v[16:17], v[182:183], v[16:17]
	v_pk_mul_f32 v[14:15], v[174:175], v[14:15]
	v_pk_mul_f32 v[12:13], v[174:175], v[12:13]
	v_pk_mul_f32 v[10:11], v[174:175], v[10:11]
	v_pk_mul_f32 v[8:9], v[174:175], v[8:9]
	v_pk_mul_f32 v[6:7], v[174:175], v[6:7]
	v_pk_mul_f32 v[4:5], v[174:175], v[4:5]
	v_pk_mul_f32 v[2:3], v[174:175], v[2:3]
	v_pk_mul_f32 v[0:1], v[182:183], v[0:1]
	v_pk_mul_f32 v[186:187], v[178:179], v[186:187]
	s_mov_b32 s17, 1
